# scan tail: o-tile staged with one bf16 pack per value pair and ds_write_b16_d16_hi for the high half (8 fewer conversions per chunk)
# baseline (speedup 1.0000x reference)
.LBB0_1092:
	v_lshlrev_b32_e32 v146, 16, v32
	v_and_b32_e32 v147, 0xffff0000, v32
	v_lshlrev_b32_e32 v148, 16, v33
	v_and_b32_e32 v149, 0xffff0000, v33
	v_xor_b32_e32 v32, 0x80000000, v1
	v_xor_b32_e32 v33, 0x80000000, v0
	v_cvt_pk_bf16_f32 v150, v33, v32
	v_xor_b32_e32 v32, 0x80000000, v2
	v_xor_b32_e32 v33, 0x80000000, v3
	v_cvt_pk_bf16_f32 v151, v32, v33
	v_xor_b32_e32 v32, 0x80000000, v4
	v_xor_b32_e32 v33, 0x80000000, v5
	v_cvt_pk_bf16_f32 v152, v32, v33
	v_xor_b32_e32 v32, 0x80000000, v6
	v_xor_b32_e32 v33, 0x80000000, v7
	v_cvt_pk_bf16_f32 v153, v32, v33
	v_xor_b32_e32 v32, 0x80000000, v8
	v_xor_b32_e32 v33, 0x80000000, v9
	v_cvt_pk_bf16_f32 v154, v32, v33
	v_xor_b32_e32 v32, 0x80000000, v10
	v_xor_b32_e32 v33, 0x80000000, v11
	v_cvt_pk_bf16_f32 v155, v32, v33
	v_xor_b32_e32 v32, 0x80000000, v12
	v_xor_b32_e32 v33, 0x80000000, v13
	v_cvt_pk_bf16_f32 v156, v32, v33
	v_xor_b32_e32 v32, 0x80000000, v14
	v_xor_b32_e32 v33, 0x80000000, v15
	v_cvt_pk_bf16_f32 v157, v32, v33
	v_xor_b32_e32 v32, 0x80000000, v16
	v_xor_b32_e32 v33, 0x80000000, v17
	v_cvt_pk_bf16_f32 v158, v32, v33
	v_xor_b32_e32 v32, 0x80000000, v18
	v_xor_b32_e32 v33, 0x80000000, v19
	v_cvt_pk_bf16_f32 v159, v32, v33
	v_xor_b32_e32 v32, 0x80000000, v20
	v_xor_b32_e32 v33, 0x80000000, v21
	v_cvt_pk_bf16_f32 v160, v32, v33
	v_xor_b32_e32 v32, 0x80000000, v22
	v_xor_b32_e32 v33, 0x80000000, v23
	v_cvt_pk_bf16_f32 v161, v32, v33
	v_xor_b32_e32 v32, 0x80000000, v28
	v_xor_b32_e32 v33, 0x80000000, v29
	s_bitcmp1_b32 s19, 0
	v_cvt_pk_bf16_f32 v162, v32, v33
	v_xor_b32_e32 v32, 0x80000000, v30
	v_xor_b32_e32 v33, 0x80000000, v31
	s_cselect_b32 s19, 0xe000, 0
	v_cvt_pk_bf16_f32 v163, v32, v33
	v_xor_b32_e32 v32, 0x80000000, v24
	v_xor_b32_e32 v33, 0x80000000, v25
	s_add_i32 s19, s19, 0
	v_cvt_pk_bf16_f32 v164, v32, v33
	v_xor_b32_e32 v32, 0x80000000, v26
	v_xor_b32_e32 v33, 0x80000000, v27
	v_and_b32_e32 v43, -16, v40
	v_cvt_pk_bf16_f32 v165, v32, v33
	v_lshlrev_b32_e32 v32, 4, v135
	v_lshl_add_u32 v33, v135, 8, s19
	v_add_u32_e32 v170, 64, v43
	v_add_u32_e32 v172, 0x80, v43
	v_add_u32_e32 v186, 0xc0, v43
	v_xad_u32 v137, v32, v43, v33
	v_xad_u32 v171, v170, v32, v33
	v_xad_u32 v172, v172, v32, v33
	v_xad_u32 v210, v186, v32, v33
	v_lshlrev_b32_e32 v138, 16, v38
	v_and_b32_e32 v139, 0xffff0000, v38
	v_lshlrev_b32_e32 v140, 16, v39
	v_and_b32_e32 v141, 0xffff0000, v39
	v_lshlrev_b32_e32 v42, 3, v40
	ds_read_b128 v[38:41], v137
	ds_read_b128 v[166:169], v171
	ds_read_b128 v[182:185], v172
	ds_read_b128 v[186:189], v210
	ds_read_b128 v[190:193], v137 offset:4096
	ds_read_b128 v[194:197], v171 offset:4096
	ds_read_b128 v[198:201], v172 offset:4096
	ds_read_b128 v[202:205], v210 offset:4096
	v_lshlrev_b32_e32 v142, 16, v34
	v_and_b32_e32 v143, 0xffff0000, v34
	v_lshlrev_b32_e32 v144, 16, v35
	v_and_b32_e32 v145, 0xffff0000, v35
	v_lshlrev_b32_e32 v34, 16, v36
	v_and_b32_e32 v35, 0xffff0000, v36
	v_lshlrev_b32_e32 v36, 16, v37
	v_and_b32_e32 v37, 0xffff0000, v37
	s_waitcnt lgkmcnt(7)
	v_mfma_f32_16x16x32_bf16 v[38:41], v[38:41], v[150:153], v[138:141]
	s_waitcnt lgkmcnt(6)
	v_mfma_f32_16x16x32_bf16 v[38:41], v[166:169], v[154:157], v[38:41]
	s_waitcnt lgkmcnt(5)
	v_mfma_f32_16x16x32_bf16 v[38:41], v[182:185], v[158:161], v[38:41]
	s_waitcnt lgkmcnt(4)
	v_mfma_f32_16x16x32_bf16 v[38:41], v[186:189], v[162:165], v[38:41]
	ds_read_b128 v[138:141], v137 offset:8192
	ds_read_b128 v[166:169], v171 offset:8192
	ds_read_b128 v[182:185], v172 offset:8192
	ds_read_b128 v[186:189], v210 offset:8192
	s_waitcnt lgkmcnt(7)
	v_mfma_f32_16x16x32_bf16 v[142:145], v[190:193], v[150:153], v[142:145]
	s_waitcnt lgkmcnt(6)
	v_mfma_f32_16x16x32_bf16 v[142:145], v[194:197], v[154:157], v[142:145]
	s_waitcnt lgkmcnt(5)
	v_mfma_f32_16x16x32_bf16 v[142:145], v[198:201], v[158:161], v[142:145]
	s_waitcnt lgkmcnt(4)
	v_mfma_f32_16x16x32_bf16 v[142:145], v[202:205], v[162:165], v[142:145]
	ds_read_b128 v[190:193], v137 offset:12288
	ds_read_b128 v[194:197], v171 offset:12288
	ds_read_b128 v[198:201], v172 offset:12288
	ds_read_b128 v[202:205], v210 offset:12288
	s_waitcnt lgkmcnt(7)
	v_mfma_f32_16x16x32_bf16 v[32:35], v[138:141], v[150:153], v[34:37]
	s_waitcnt lgkmcnt(6)
	v_mfma_f32_16x16x32_bf16 v[32:35], v[166:169], v[154:157], v[32:35]
	s_waitcnt lgkmcnt(5)
	v_mfma_f32_16x16x32_bf16 v[32:35], v[182:185], v[158:161], v[32:35]
	s_waitcnt lgkmcnt(4)
	v_mfma_f32_16x16x32_bf16 v[32:35], v[186:189], v[162:165], v[32:35]
	ds_read_b128 v[138:141], v137 offset:16384
	ds_read_b128 v[166:169], v171 offset:16384
	ds_read_b128 v[182:185], v172 offset:16384
	ds_read_b128 v[186:189], v210 offset:16384
	s_waitcnt lgkmcnt(7)
	v_mfma_f32_16x16x32_bf16 v[146:149], v[190:193], v[150:153], v[146:149]
	s_waitcnt lgkmcnt(6)
	v_mfma_f32_16x16x32_bf16 v[146:149], v[194:197], v[154:157], v[146:149]
	s_waitcnt lgkmcnt(5)
	v_mfma_f32_16x16x32_bf16 v[146:149], v[198:201], v[158:161], v[146:149]
	s_waitcnt lgkmcnt(4)
	v_mfma_f32_16x16x32_bf16 v[146:149], v[202:205], v[162:165], v[146:149]
	ds_read_b128 v[190:193], v137 offset:20480
	ds_read_b128 v[194:197], v171 offset:20480
	ds_read_b128 v[198:201], v172 offset:20480
	ds_read_b128 v[202:205], v210 offset:20480
	v_xor_b32_e32 v153, 0x80008000, v153
	v_xor_b32_e32 v152, 0x80008000, v152
	v_xor_b32_e32 v151, 0x80008000, v151
	v_xor_b32_e32 v150, 0x80008000, v150
	v_xor_b32_e32 v157, 0x80008000, v157
	v_xor_b32_e32 v156, 0x80008000, v156
	s_waitcnt lgkmcnt(7)
	v_mfma_f32_16x16x32_bf16 v[138:141], v[138:141], v[150:153], 0
	v_xor_b32_e32 v155, 0x80008000, v155
	v_xor_b32_e32 v154, 0x80008000, v154
	v_xor_b32_e32 v161, 0x80008000, v161
	v_xor_b32_e32 v160, 0x80008000, v160
	s_waitcnt lgkmcnt(6)
	v_mfma_f32_16x16x32_bf16 v[138:141], v[166:169], v[154:157], v[138:141]
	v_xor_b32_e32 v159, 0x80008000, v159
	v_xor_b32_e32 v158, 0x80008000, v158
	v_xor_b32_e32 v165, 0x80008000, v165
	v_xor_b32_e32 v164, 0x80008000, v164
	s_waitcnt lgkmcnt(5)
	v_mfma_f32_16x16x32_bf16 v[138:141], v[182:185], v[158:161], v[138:141]
	v_xor_b32_e32 v163, 0x80008000, v163
	v_xor_b32_e32 v162, 0x80008000, v162
	s_waitcnt lgkmcnt(4)
	s_nop 0
	v_mfma_f32_16x16x32_bf16 v[138:141], v[186:189], v[162:165], v[138:141]
	ds_read_b128 v[166:169], v137 offset:24576
	ds_read_b128 v[182:185], v171 offset:24576
	ds_read_b128 v[186:189], v172 offset:24576
	ds_read_b128 v[206:209], v210 offset:24576
	s_waitcnt lgkmcnt(7)
	v_mfma_f32_16x16x32_bf16 v[190:193], v[190:193], v[150:153], 0
	s_waitcnt lgkmcnt(6)
	v_mfma_f32_16x16x32_bf16 v[190:193], v[194:197], v[154:157], v[190:193]
	s_waitcnt lgkmcnt(5)
	v_mfma_f32_16x16x32_bf16 v[190:193], v[198:201], v[158:161], v[190:193]
	s_waitcnt lgkmcnt(4)
	v_mfma_f32_16x16x32_bf16 v[190:193], v[202:205], v[162:165], v[190:193]
	ds_read_b128 v[194:197], v137 offset:28672
	ds_read_b128 v[198:201], v171 offset:28672
	ds_read_b128 v[202:205], v172 offset:28672
	ds_read_b128 v[210:213], v210 offset:28672
	s_waitcnt lgkmcnt(7)
	v_mfma_f32_16x16x32_bf16 v[166:169], v[166:169], v[150:153], 0
	v_and_b32_e32 v36, 0x70, v42
	v_lshl_add_u32 v37, v135, 7, s19
	v_xad_u32 v137, v36, v43, v37
	s_waitcnt lgkmcnt(6)
	v_mfma_f32_16x16x32_bf16 v[166:169], v[182:185], v[154:157], v[166:169]
	v_xad_u32 v170, v170, v36, v37
	ds_read_b128 v[182:185], v137 offset:49152
	s_waitcnt lgkmcnt(6)
	v_mfma_f32_16x16x32_bf16 v[166:169], v[186:189], v[158:161], v[166:169]
	s_waitcnt lgkmcnt(5)
	v_mfma_f32_16x16x32_bf16 v[166:169], v[206:209], v[162:165], v[166:169]
	ds_read_b128 v[186:189], v170 offset:49152
	ds_read_b128 v[206:209], v137 offset:51200
	ds_read_b128 v[230:233], v170 offset:51200
	s_waitcnt lgkmcnt(7)
	v_mfma_f32_16x16x32_bf16 v[150:153], v[194:197], v[150:153], 0
	s_waitcnt lgkmcnt(6)
	v_mfma_f32_16x16x32_bf16 v[150:153], v[198:201], v[154:157], v[150:153]
	s_waitcnt lgkmcnt(5)
	v_mfma_f32_16x16x32_bf16 v[150:153], v[202:205], v[158:161], v[150:153]
	ds_read_b128 v[154:157], v137 offset:53248
	ds_read_b128 v[158:161], v137 offset:55296
	ds_read_b128 v[194:197], v170 offset:53248
	ds_read_b128 v[198:201], v170 offset:55296
	s_waitcnt lgkmcnt(8)
	v_mfma_f32_16x16x32_bf16 v[150:153], v[210:213], v[162:165], v[150:153]
	v_cvt_pk_bf16_f32 v162, v38, v39
	v_cvt_pk_bf16_f32 v163, v40, v41
	v_cvt_pk_bf16_f32 v164, v142, v143
	v_cvt_pk_bf16_f32 v165, v144, v145
	v_cvt_pk_bf16_f32 v142, v32, v33
	v_cvt_pk_bf16_f32 v143, v34, v35
	s_waitcnt lgkmcnt(7)
	v_mfma_f32_16x16x32_bf16 v[36:39], v[182:185], v[162:165], v[138:141]
	v_cvt_pk_bf16_f32 v144, v146, v147
	v_cvt_pk_bf16_f32 v145, v148, v149
	s_waitcnt lgkmcnt(5)
	v_mfma_f32_16x16x32_bf16 v[32:35], v[206:209], v[162:165], v[190:193]
	v_mfma_f32_16x16x32_bf16 v[138:141], v[186:189], v[142:145], v[36:39]
	ds_read_b128 v[146:149], v137 offset:32768
	ds_read_b128 v[182:185], v137 offset:34816
	ds_read_b128 v[186:189], v170 offset:32768
	ds_read_b128 v[190:193], v170 offset:34816
	s_waitcnt lgkmcnt(8)
	v_mfma_f32_16x16x32_bf16 v[40:43], v[230:233], v[142:145], v[32:35]
	s_waitcnt lgkmcnt(7)
	v_mfma_f32_16x16x32_bf16 v[32:35], v[154:157], v[162:165], v[166:169]
	s_waitcnt lgkmcnt(5)
	v_mfma_f32_16x16x32_bf16 v[36:39], v[194:197], v[142:145], v[32:35]
	v_mfma_f32_16x16x32_bf16 v[32:35], v[158:161], v[162:165], v[150:153]
	s_nop 2
	ds_read_b128 v[150:153], v137 offset:36864
	ds_read_b128 v[154:157], v170 offset:36864
	ds_read_b128 v[158:161], v137 offset:38912
	ds_read_b128 v[166:169], v170 offset:38912
	s_waitcnt lgkmcnt(8)
	v_mfma_f32_16x16x32_bf16 v[32:35], v[198:201], v[142:145], v[32:35]
	v_mul_f32_e64 v2, v124, v2
	v_mul_f32_e64 v3, v124, v3
	v_pk_mul_f32 v[0:1], v[124:125], v[0:1] op_sel_hi:[0,1]
	v_pk_mul_f32 v[6:7], v[124:125], v[6:7] op_sel_hi:[0,1]
	v_pk_mul_f32 v[4:5], v[124:125], v[4:5] op_sel_hi:[0,1]
	s_waitcnt lgkmcnt(7)
	v_mfma_f32_16x16x32_bf16 v[0:3], v[146:149], v[162:165], v[0:3]
	s_waitcnt lgkmcnt(6)
	v_mfma_f32_16x16x32_bf16 v[4:7], v[182:185], v[162:165], v[4:7]
	s_waitcnt lgkmcnt(5)
	v_mfma_f32_16x16x32_bf16 v[0:3], v[186:189], v[142:145], v[0:3]
	s_waitcnt lgkmcnt(4)
	v_mfma_f32_16x16x32_bf16 v[4:7], v[190:193], v[142:145], v[4:7]
	ds_read_b128 v[146:149], v137 offset:40960
	ds_read_b128 v[182:185], v170 offset:40960
	ds_read_b128 v[186:189], v137 offset:43008
	ds_read_b128 v[190:193], v170 offset:43008
	v_pk_mul_f32 v[10:11], v[124:125], v[10:11] op_sel_hi:[0,1]
	v_pk_mul_f32 v[8:9], v[124:125], v[8:9] op_sel_hi:[0,1]
	v_pk_mul_f32 v[14:15], v[124:125], v[14:15] op_sel_hi:[0,1]
	v_pk_mul_f32 v[12:13], v[124:125], v[12:13] op_sel_hi:[0,1]
	s_waitcnt lgkmcnt(7)
	v_mfma_f32_16x16x32_bf16 v[8:11], v[150:153], v[162:165], v[8:11]
	s_waitcnt lgkmcnt(5)
	v_mfma_f32_16x16x32_bf16 v[12:15], v[158:161], v[162:165], v[12:15]
	v_mfma_f32_16x16x32_bf16 v[8:11], v[154:157], v[142:145], v[8:11]
	s_waitcnt lgkmcnt(4)
	v_mfma_f32_16x16x32_bf16 v[12:15], v[166:169], v[142:145], v[12:15]
	ds_read_b128 v[150:153], v137 offset:45056
	ds_read_b128 v[154:157], v170 offset:45056
	ds_read_b128 v[158:161], v137 offset:47104
	ds_read_b128 v[166:169], v170 offset:47104
	v_pk_mul_f32 v[18:19], v[124:125], v[18:19] op_sel_hi:[0,1]
	v_pk_mul_f32 v[16:17], v[124:125], v[16:17] op_sel_hi:[0,1]
	v_pk_mul_f32 v[22:23], v[124:125], v[22:23] op_sel_hi:[0,1]
	v_pk_mul_f32 v[20:21], v[124:125], v[20:21] op_sel_hi:[0,1]
	s_waitcnt lgkmcnt(7)
	v_mfma_f32_16x16x32_bf16 v[16:19], v[146:149], v[162:165], v[16:19]
	s_waitcnt lgkmcnt(5)
	v_mfma_f32_16x16x32_bf16 v[20:23], v[186:189], v[162:165], v[20:23]
	v_mfma_f32_16x16x32_bf16 v[16:19], v[182:185], v[142:145], v[16:19]
	s_waitcnt lgkmcnt(4)
	v_mfma_f32_16x16x32_bf16 v[20:23], v[190:193], v[142:145], v[20:23]
	s_ashr_i32 s19, s18, 31
	s_lshl_b64 s[20:21], s[18:19], 11
	v_pk_mul_f32 v[30:31], v[124:125], v[30:31] op_sel_hi:[0,1]
	v_pk_mul_f32 v[28:29], v[124:125], v[28:29] op_sel_hi:[0,1]
	v_pk_mul_f32 v[26:27], v[124:125], v[26:27] op_sel_hi:[0,1]
	v_pk_mul_f32 v[24:25], v[124:125], v[24:25] op_sel_hi:[0,1]
	s_add_u32 s20, s23, s20
	s_addc_u32 s21, s62, s21
	s_waitcnt lgkmcnt(3)
	v_mfma_f32_16x16x32_bf16 v[28:31], v[150:153], v[162:165], v[28:31]
	s_andn2_b64 vcc, exec, s[12:13]
	s_waitcnt lgkmcnt(1)
	v_mfma_f32_16x16x32_bf16 v[24:27], v[158:161], v[162:165], v[24:27]
	v_mfma_f32_16x16x32_bf16 v[28:31], v[154:157], v[142:145], v[28:31]
	s_waitcnt lgkmcnt(0)
	v_mfma_f32_16x16x32_bf16 v[24:27], v[166:169], v[142:145], v[24:27]
	s_cbranch_vccnz .Lscan_smp
	s_bitcmp1_b32 s64, 0
	s_mov_b32 s65, 0x20010
	s_cselect_b32 s65, 0x1c000, s65
	v_lshlrev_b32_e32 v137, 10, v136
	s_lshl_b32 s66, s28, 1
	v_lshl_add_u32 v137, v135, 1, v137
	v_lshlrev_b32_e32 v124, 5, v136
	v_lshlrev_b32_e32 v171, 11, v136
	v_xor_b32_e32 v124, s66, v124
	v_add3_u32 v137, v137, v124, s65
	v_lshl_add_u32 v171, v135, 4, v171
	v_cvt_pk_bf16_f32 v124, v138, v139
	ds_write_b16 v137, v124
	ds_write_b16_d16_hi v137, v124 offset:256
	v_cvt_pk_bf16_f32 v124, v140, v141
	ds_write_b16 v137, v124 offset:512
	ds_write_b16_d16_hi v137, v124 offset:768
	v_cvt_pk_bf16_f32 v124, v40, v41
	ds_write_b16 v137, v124 offset:4096
	ds_write_b16_d16_hi v137, v124 offset:4352
	v_cvt_pk_bf16_f32 v124, v42, v43
	ds_write_b16 v137, v124 offset:4608
	ds_write_b16_d16_hi v137, v124 offset:4864
	v_cvt_pk_bf16_f32 v124, v36, v37
	ds_write_b16 v137, v124 offset:8192
	ds_write_b16_d16_hi v137, v124 offset:8448
	v_cvt_pk_bf16_f32 v124, v38, v39
	ds_write_b16 v137, v124 offset:8704
	ds_write_b16_d16_hi v137, v124 offset:8960
	v_cvt_pk_bf16_f32 v124, v32, v33
	ds_write_b16 v137, v124 offset:12288
	ds_write_b16_d16_hi v137, v124 offset:12544
	v_cvt_pk_bf16_f32 v124, v34, v35
	ds_write_b16 v137, v124 offset:12800
	ds_write_b16_d16_hi v137, v124 offset:13056
	s_lshl_b32 s66, s28, 1
	s_and_b32 s66, s66, 0x60
	v_lshlrev_b32_e32 v170, 4, v125
	v_xor_b32_e32 v170, s66, v170
	s_lshl_b32 s66, s28, 6
	s_add_i32 s66, s66, s65
	v_add_u32_e32 v170, s66, v170
	s_lshl_b32 s66, s28, 9
	v_add_u32_e32 v171, s66, v171
	s_add_u32 s58, s20, 0x10000
	s_addc_u32 s59, s21, 0
	s_add_i32 s18, s18, 64
	s_waitcnt vmcnt(0) lgkmcnt(0)
	s_barrier
	ds_read_b128 v[146:149], v170
	ds_read_b128 v[150:153], v170 offset:8192
	v_permlane16_swap_b32_e32 v126, v128
	v_permlane16_swap_b32_e32 v127, v129
	v_permlane16_swap_b32_e32 v130, v132
	v_permlane16_swap_b32_e32 v131, v133
	s_nop 1
	v_permlane32_swap_b32_e32 v126, v128
	v_permlane32_swap_b32_e32 v127, v129
	v_permlane32_swap_b32_e32 v130, v132
	v_permlane32_swap_b32_e32 v131, v133
	s_nop 1
	v_mov_b64_e32 v[38:39], v[126:127]
	v_mov_b64_e32 v[34:35], v[128:129]
	v_mov_b64_e32 v[36:37], v[130:131]
	v_mov_b64_e32 v[32:33], v[132:133]
	v_mov_b32_e32 v124, v134
	s_cmp_eq_u32 s22, s64
	s_mov_b32 s19, s64
	s_waitcnt lgkmcnt(1)
	global_store_dwordx4 v171, v[146:149], s[20:21]
	s_waitcnt lgkmcnt(0)
	global_store_dwordx4 v171, v[150:153], s[58:59]
	s_cbranch_scc1 .LBB0_1083
	s_branch .LBB0_1090
